# k23
# baseline (speedup 1.0000x reference)
; #define PG8_STAGE(bufoff, gbase, voff) do { _Pragma("unroll") for (int _i = 0; _i < 2; ++_i) \
;         __builtin_amdgcn_global_load_lds((const unsigned*)((const char*)(gbase) + (voff)[_i]), (LAS unsigned*)(lds + (bufoff) + ldsw + _i * 8192), 16, 0, 0); } while (0)
; #define PG8_LDA(dst, b, h) do { _Pragma("unroll") for (int m = 0; m < 4; ++m) _Pragma("unroll") for (int k = 0; k < 2; ++k) dst[m][k] = *(const LAS bf16x8*)(lds + PG8_SA(b, h) + aoff + m * 2048 + k * 1024); } while (0)
; #define PG8_LDB(dst, b, h) do { _Pragma("unroll") for (int n = 0; n < 2; ++n) _Pragma("unroll") for (int k = 0; k < 2; ++k) dst[n][k] = *(const LAS bf16x8*)(lds + PG8_SB(b, h) + boff + n * 2048 + k * 1024); } while (0)
; #define PG8_MMA(ai, bj, At, Bt) do { __builtin_amdgcn_s_setprio(1); _Pragma("unroll") for (int m = 0; m < 4; ++m) _Pragma("unroll") for (int n = 0; n < 2; ++n) _Pragma("unroll") for (int k = 0; k < 2; ++k) \
;         acc[ai][bj][m][n] = __builtin_amdgcn_mfma_f32_16x16x32_bf16(Bt[n][k], At[m][k], acc[ai][bj][m][n], 0, 0, 0); __builtin_amdgcn_s_setprio(0); } while (0)
; #define PG8_WAIT_V(n) asm volatile("s_waitcnt vmcnt(" #n ")" ::: "memory")
; #define PG8_WAIT_L(n) asm volatile("s_waitcnt lgkmcnt(" #n ")" ::: "memory")
; #define PG8_BAR __builtin_amdgcn_s_barrier()
; #define PG8_SCHED __builtin_amdgcn_sched_barrier(0)
; template <class Epi, class Sched>
; __device__ __forceinline__ void gemm_phase(LAS unsigned char* lds, const Gemm g, const Sched& S, const Epi& E, int wid_) {
;     ...
;             const bool last = (t == nt - 2);
;             const char* a1 = cA + (size_t)(t + 1) * kstep;
;             const char* a2 = last ? nA : cA + (size_t)(t + 2) * kstep; const char* b2 = last ? nB : cB + (size_t)(t + 2) * kstep;
;             const char* a3 = a2 + kstep; const char* b3 = b2 + kstep;
;             PG8_LDB(B0, 0, 0); PG8_LDB(B1, 0, 1); PG8_SCHED; PG8_LDA(At, 0, 0); PG8_STAGE(PG8_SA(1, 1), a1 + hstepA, voffA);
;             PG8_WAIT_V(8); PG8_WAIT_L(0); PG8_BAR; PG8_MMA(0, 0, At, B0); PG8_MMA(0, 1, At, B1); PG8_BAR; PG8_SCHED;
;             PG8_LDA(At, 0, 1); PG8_STAGE(PG8_SB(0, 0), b2, voffB); PG8_STAGE(PG8_SB(0, 1), b2 + hstepB, voffB); PG8_STAGE(PG8_SA(0, 0), a2, voffA);
;             PG8_WAIT_V(8); PG8_WAIT_L(0); PG8_BAR; PG8_MMA(1, 0, At, B0); PG8_MMA(1, 1, At, B1); PG8_BAR; PG8_SCHED;
.LBB0_348:
	s_add_u32 s12, s6, 0xfff00080
	s_addc_u32 s14, s7, -1
	s_add_i32 s34, 0, 0x10000
	s_cmp_eq_u32 s33, 60
	s_cselect_b32 s37, s23, s14
	s_cselect_b32 s36, s68, s12
	v_add_u32_e32 v0, s34, v148
	s_cselect_b32 s31, s69, s54
	s_cselect_b32 s30, s80, s81
	s_add_i32 s12, 0, 0x14000
	ds_read_b128 v[142:145], v0
	ds_read_b128 v[150:153], v0 offset:1024
	ds_read_b128 v[154:157], v0 offset:2048
	ds_read_b128 v[158:161], v0 offset:3072
	v_add_u32_e32 v0, s12, v148
	ds_read_b128 v[162:165], v0
	ds_read_b128 v[166:169], v0 offset:1024
	ds_read_b128 v[170:173], v0 offset:2048
	ds_read_b128 v[174:177], v0 offset:3072
	s_add_i32 m0, s41, 0xc000
	ds_read_b128 v[178:181], v149
	ds_read_b128 v[182:185], v149 offset:1024
	ds_read_b128 v[186:189], v149 offset:2048
	ds_read_b128 v[190:193], v149 offset:3072
	ds_read_b128 v[194:197], v149 offset:4096
	ds_read_b128 v[198:201], v149 offset:5120
	ds_read_b128 v[202:205], v149 offset:6144
	ds_read_b128 v[212:215], v149 offset:7168
	global_load_lds_dwordx4 v138, s[6:7]
	s_add_i32 m0, s41, 0xe000
	s_nop 0
	global_load_lds_dwordx4 v140, s[6:7]
	s_waitcnt vmcnt(8)
	s_waitcnt lgkmcnt(0)
	s_barrier
	s_setprio 1
	s_waitcnt lgkmcnt(0)
	v_mfma_f32_16x16x32_bf16 v[126:129], v[142:145], v[178:181], v[126:129]
	v_mfma_f32_16x16x32_bf16 v[122:125], v[154:157], v[178:181], v[122:125]
	v_mfma_f32_16x16x32_bf16 v[110:113], v[142:145], v[186:189], v[110:113]
	v_mfma_f32_16x16x32_bf16 v[106:109], v[154:157], v[186:189], v[106:109]
	v_mfma_f32_16x16x32_bf16 v[94:97], v[142:145], v[194:197], v[94:97]
	v_mfma_f32_16x16x32_bf16 v[90:93], v[154:157], v[194:197], v[90:93]
	v_mfma_f32_16x16x32_bf16 v[78:81], v[142:145], v[202:205], v[78:81]
	v_mfma_f32_16x16x32_bf16 v[74:77], v[154:157], v[202:205], v[74:77]
	v_mfma_f32_16x16x32_bf16 v[126:129], v[150:153], v[182:185], v[126:129]
	v_mfma_f32_16x16x32_bf16 v[122:125], v[158:161], v[182:185], v[122:125]
	v_mfma_f32_16x16x32_bf16 v[110:113], v[150:153], v[190:193], v[110:113]
	v_mfma_f32_16x16x32_bf16 v[106:109], v[158:161], v[190:193], v[106:109]
	v_mfma_f32_16x16x32_bf16 v[94:97], v[150:153], v[198:201], v[94:97]
	v_mfma_f32_16x16x32_bf16 v[90:93], v[158:161], v[198:201], v[90:93]
	v_mfma_f32_16x16x32_bf16 v[78:81], v[150:153], v[212:215], v[78:81]
	v_mfma_f32_16x16x32_bf16 v[74:77], v[158:161], v[212:215], v[74:77]
	s_setprio 0
	s_setprio 1
	v_mfma_f32_16x16x32_bf16 v[118:121], v[162:165], v[178:181], v[118:121]
	v_mfma_f32_16x16x32_bf16 v[114:117], v[170:173], v[178:181], v[114:117]
	v_mfma_f32_16x16x32_bf16 v[102:105], v[162:165], v[186:189], v[102:105]
	v_mfma_f32_16x16x32_bf16 v[98:101], v[170:173], v[186:189], v[98:101]
	v_mfma_f32_16x16x32_bf16 v[86:89], v[162:165], v[194:197], v[86:89]
	v_mfma_f32_16x16x32_bf16 v[82:85], v[170:173], v[194:197], v[82:85]
	v_mfma_f32_16x16x32_bf16 v[70:73], v[162:165], v[202:205], v[70:73]
	v_mfma_f32_16x16x32_bf16 v[66:69], v[170:173], v[202:205], v[66:69]
	v_mfma_f32_16x16x32_bf16 v[118:121], v[166:169], v[182:185], v[118:121]
	v_mfma_f32_16x16x32_bf16 v[114:117], v[174:177], v[182:185], v[114:117]
	v_mfma_f32_16x16x32_bf16 v[102:105], v[166:169], v[190:193], v[102:105]
	v_mfma_f32_16x16x32_bf16 v[98:101], v[174:177], v[190:193], v[98:101]
	v_mfma_f32_16x16x32_bf16 v[86:89], v[166:169], v[198:201], v[86:89]
	v_mfma_f32_16x16x32_bf16 v[82:85], v[174:177], v[198:201], v[82:85]
	v_mfma_f32_16x16x32_bf16 v[70:73], v[166:169], v[212:215], v[70:73]
	v_mfma_f32_16x16x32_bf16 v[66:69], v[174:177], v[212:215], v[66:69]
	s_setprio 0
	s_barrier
	s_add_i32 s14, s34, s39
	s_mov_b32 m0, s14
	ds_read_b128 v[178:181], v149 offset:16384
	ds_read_b128 v[182:185], v149 offset:17408
	ds_read_b128 v[186:189], v149 offset:18432
	ds_read_b128 v[190:193], v149 offset:19456
	ds_read_b128 v[194:197], v149 offset:20480
	ds_read_b128 v[198:201], v149 offset:21504
	ds_read_b128 v[202:205], v149 offset:22528
	ds_read_b128 v[212:215], v149 offset:23552
	global_load_lds_dwordx4 v134, s[30:31]
	s_add_i32 m0, s14, 0x2000
	s_add_u32 s34, s30, 0x100000
	s_addc_u32 s35, s31, 0
	s_add_i32 s12, s12, s39
	global_load_lds_dwordx4 v130, s[30:31]
	s_mov_b32 m0, s12
	s_nop 0
	global_load_lds_dwordx4 v134, s[34:35]
	s_add_i32 m0, s12, 0x2000
	s_nop 0
	global_load_lds_dwordx4 v130, s[34:35]
	s_mov_b32 m0, s41
	s_nop 0
	global_load_lds_dwordx4 v136, s[36:37]
	s_mov_b32 m0, s42
	s_nop 0
	global_load_lds_dwordx4 v132, s[36:37]
	s_waitcnt vmcnt(8)
	s_waitcnt lgkmcnt(0)
	s_barrier
	s_setprio 1
	s_waitcnt lgkmcnt(0)
	v_mfma_f32_16x16x32_bf16 v[62:65], v[142:145], v[178:181], v[62:65]
	v_mfma_f32_16x16x32_bf16 v[58:61], v[154:157], v[178:181], v[58:61]
	v_mfma_f32_16x16x32_bf16 v[46:49], v[142:145], v[186:189], v[46:49]
	v_mfma_f32_16x16x32_bf16 v[42:45], v[154:157], v[186:189], v[42:45]
	v_mfma_f32_16x16x32_bf16 v[30:33], v[142:145], v[194:197], v[30:33]
	v_mfma_f32_16x16x32_bf16 v[26:29], v[154:157], v[194:197], v[26:29]
	v_mfma_f32_16x16x32_bf16 v[14:17], v[142:145], v[202:205], v[14:17]
	v_mfma_f32_16x16x32_bf16 v[10:13], v[154:157], v[202:205], v[10:13]
	v_mfma_f32_16x16x32_bf16 v[62:65], v[150:153], v[182:185], v[62:65]
	v_mfma_f32_16x16x32_bf16 v[58:61], v[158:161], v[182:185], v[58:61]
	v_mfma_f32_16x16x32_bf16 v[46:49], v[150:153], v[190:193], v[46:49]
	v_mfma_f32_16x16x32_bf16 v[42:45], v[158:161], v[190:193], v[42:45]
	v_mfma_f32_16x16x32_bf16 v[30:33], v[150:153], v[198:201], v[30:33]
	v_mfma_f32_16x16x32_bf16 v[26:29], v[158:161], v[198:201], v[26:29]
	v_mfma_f32_16x16x32_bf16 v[14:17], v[150:153], v[212:215], v[14:17]
	v_mfma_f32_16x16x32_bf16 v[10:13], v[158:161], v[212:215], v[10:13]
	s_setprio 0
	s_setprio 1
	v_mfma_f32_16x16x32_bf16 v[54:57], v[162:165], v[178:181], v[54:57]
	v_mfma_f32_16x16x32_bf16 v[50:53], v[170:173], v[178:181], v[50:53]
	v_mfma_f32_16x16x32_bf16 v[38:41], v[162:165], v[186:189], v[38:41]
	v_mfma_f32_16x16x32_bf16 v[34:37], v[170:173], v[186:189], v[34:37]
	v_mfma_f32_16x16x32_bf16 v[22:25], v[162:165], v[194:197], v[22:25]
	v_mfma_f32_16x16x32_bf16 v[18:21], v[170:173], v[194:197], v[18:21]
	v_mfma_f32_16x16x32_bf16 v[6:9], v[162:165], v[202:205], v[6:9]
	v_mfma_f32_16x16x32_bf16 v[2:5], v[170:173], v[202:205], v[2:5]
	v_mfma_f32_16x16x32_bf16 v[54:57], v[166:169], v[182:185], v[54:57]
	v_mfma_f32_16x16x32_bf16 v[50:53], v[174:177], v[182:185], v[50:53]
	v_mfma_f32_16x16x32_bf16 v[38:41], v[166:169], v[190:193], v[38:41]
	v_mfma_f32_16x16x32_bf16 v[34:37], v[174:177], v[190:193], v[34:37]
	v_mfma_f32_16x16x32_bf16 v[22:25], v[166:169], v[198:201], v[22:25]
	v_mfma_f32_16x16x32_bf16 v[18:21], v[174:177], v[198:201], v[18:21]
	v_mfma_f32_16x16x32_bf16 v[6:9], v[166:169], v[212:215], v[6:9]
	v_mfma_f32_16x16x32_bf16 v[2:5], v[174:177], v[212:215], v[2:5]
	s_setprio 0
	s_barrier
; #define PG8_STAGE(bufoff, gbase, voff) do { _Pragma("unroll") for (int _i = 0; _i < 2; ++_i) \
;         __builtin_amdgcn_global_load_lds((const unsigned*)((const char*)(gbase) + (voff)[_i]), (LAS unsigned*)(lds + (bufoff) + ldsw + _i * 8192), 16, 0, 0); } while (0)
; #define PG8_LDA(dst, b, h) do { _Pragma("unroll") for (int m = 0; m < 4; ++m) _Pragma("unroll") for (int k = 0; k < 2; ++k) dst[m][k] = *(const LAS bf16x8*)(lds + PG8_SA(b, h) + aoff + m * 2048 + k * 1024); } while (0)
; #define PG8_LDB(dst, b, h) do { _Pragma("unroll") for (int n = 0; n < 2; ++n) _Pragma("unroll") for (int k = 0; k < 2; ++k) dst[n][k] = *(const LAS bf16x8*)(lds + PG8_SB(b, h) + boff + n * 2048 + k * 1024); } while (0)
; #define PG8_MMA(ai, bj, At, Bt) do { __builtin_amdgcn_s_setprio(1); _Pragma("unroll") for (int m = 0; m < 4; ++m) _Pragma("unroll") for (int n = 0; n < 2; ++n) _Pragma("unroll") for (int k = 0; k < 2; ++k) \
;         acc[ai][bj][m][n] = __builtin_amdgcn_mfma_f32_16x16x32_bf16(Bt[n][k], At[m][k], acc[ai][bj][m][n], 0, 0, 0); __builtin_amdgcn_s_setprio(0); } while (0)
; #define PG8_WAIT_V(n) asm volatile("s_waitcnt vmcnt(" #n ")" ::: "memory")
; #define PG8_WAIT_L(n) asm volatile("s_waitcnt lgkmcnt(" #n ")" ::: "memory")
; #define PG8_BAR __builtin_amdgcn_s_barrier()
; #define PG8_SCHED __builtin_amdgcn_sched_barrier(0)
; template <class Epi, class Sched>
; __device__ __forceinline__ void gemm_phase(LAS unsigned char* lds, const Gemm g, const Sched& S, const Epi& E, int wid_) {
;     ...
;             PG8_LDB(B0, 1, 0); PG8_LDB(B1, 1, 1); PG8_SCHED; PG8_LDA(At, 1, 0); PG8_STAGE(PG8_SA(0, 1), a2 + hstepA, voffA);
;             PG8_WAIT_V(8); PG8_WAIT_L(0); PG8_BAR; PG8_MMA(0, 0, At, B0); PG8_MMA(0, 1, At, B1); PG8_BAR; PG8_SCHED;
;             PG8_LDA(At, 1, 1); PG8_STAGE(PG8_SB(1, 0), b3, voffB); PG8_STAGE(PG8_SB(1, 1), b3 + hstepB, voffB); PG8_STAGE(PG8_SA(1, 0), a3, voffA);
;             PG8_WAIT_V(8); PG8_WAIT_L(0); PG8_BAR; PG8_MMA(1, 0, At, B0); PG8_MMA(1, 1, At, B1); PG8_BAR; PG8_SCHED;
;         }
	s_add_i32 s12, 0, 0x18000
	v_add_u32_e32 v0, s12, v148
	s_add_i32 s14, 0, 0x1c000
	ds_read_b128 v[142:145], v0
	ds_read_b128 v[150:153], v0 offset:1024
	ds_read_b128 v[154:157], v0 offset:2048
	ds_read_b128 v[158:161], v0 offset:3072
	v_add_u32_e32 v0, s14, v148
	ds_read_b128 v[162:165], v0
	ds_read_b128 v[166:169], v0 offset:1024
	ds_read_b128 v[170:173], v0 offset:2048
	ds_read_b128 v[174:177], v0 offset:3072
	s_add_u32 s34, s36, 0x100000
	s_addc_u32 s35, s37, 0
	s_mov_b32 m0, s43
	ds_read_b128 v[178:181], v149 offset:32768
	ds_read_b128 v[182:185], v149 offset:33792
	ds_read_b128 v[186:189], v149 offset:34816
	ds_read_b128 v[190:193], v149 offset:35840
	ds_read_b128 v[194:197], v149 offset:36864
	ds_read_b128 v[198:201], v149 offset:37888
	ds_read_b128 v[202:205], v149 offset:38912
	ds_read_b128 v[212:215], v149 offset:39936
	global_load_lds_dwordx4 v136, s[34:35]
	s_mov_b32 m0, s44
	s_nop 0
	global_load_lds_dwordx4 v132, s[34:35]
	s_waitcnt vmcnt(8)
	s_waitcnt lgkmcnt(0)
	s_barrier
	s_setprio 1
	s_waitcnt lgkmcnt(0)
	v_mfma_f32_16x16x32_bf16 v[126:129], v[142:145], v[178:181], v[126:129]
	v_mfma_f32_16x16x32_bf16 v[122:125], v[154:157], v[178:181], v[122:125]
	v_mfma_f32_16x16x32_bf16 v[110:113], v[142:145], v[186:189], v[110:113]
	v_mfma_f32_16x16x32_bf16 v[106:109], v[154:157], v[186:189], v[106:109]
	v_mfma_f32_16x16x32_bf16 v[94:97], v[142:145], v[194:197], v[94:97]
	v_mfma_f32_16x16x32_bf16 v[90:93], v[154:157], v[194:197], v[90:93]
	v_mfma_f32_16x16x32_bf16 v[78:81], v[142:145], v[202:205], v[78:81]
	v_mfma_f32_16x16x32_bf16 v[74:77], v[154:157], v[202:205], v[74:77]
	v_mfma_f32_16x16x32_bf16 v[126:129], v[150:153], v[182:185], v[126:129]
	v_mfma_f32_16x16x32_bf16 v[122:125], v[158:161], v[182:185], v[122:125]
	v_mfma_f32_16x16x32_bf16 v[110:113], v[150:153], v[190:193], v[110:113]
	v_mfma_f32_16x16x32_bf16 v[106:109], v[158:161], v[190:193], v[106:109]
	v_mfma_f32_16x16x32_bf16 v[94:97], v[150:153], v[198:201], v[94:97]
	v_mfma_f32_16x16x32_bf16 v[90:93], v[158:161], v[198:201], v[90:93]
	v_mfma_f32_16x16x32_bf16 v[78:81], v[150:153], v[212:215], v[78:81]
	v_mfma_f32_16x16x32_bf16 v[74:77], v[158:161], v[212:215], v[74:77]
	s_setprio 0
	s_setprio 1
	v_mfma_f32_16x16x32_bf16 v[118:121], v[162:165], v[178:181], v[118:121]
	v_mfma_f32_16x16x32_bf16 v[114:117], v[170:173], v[178:181], v[114:117]
	v_mfma_f32_16x16x32_bf16 v[102:105], v[162:165], v[186:189], v[102:105]
	v_mfma_f32_16x16x32_bf16 v[98:101], v[170:173], v[186:189], v[98:101]
	v_mfma_f32_16x16x32_bf16 v[86:89], v[162:165], v[194:197], v[86:89]
	v_mfma_f32_16x16x32_bf16 v[82:85], v[170:173], v[194:197], v[82:85]
	v_mfma_f32_16x16x32_bf16 v[70:73], v[162:165], v[202:205], v[70:73]
	v_mfma_f32_16x16x32_bf16 v[66:69], v[170:173], v[202:205], v[66:69]
	v_mfma_f32_16x16x32_bf16 v[118:121], v[166:169], v[182:185], v[118:121]
	v_mfma_f32_16x16x32_bf16 v[114:117], v[174:177], v[182:185], v[114:117]
	v_mfma_f32_16x16x32_bf16 v[102:105], v[166:169], v[190:193], v[102:105]
	v_mfma_f32_16x16x32_bf16 v[98:101], v[174:177], v[190:193], v[98:101]
	v_mfma_f32_16x16x32_bf16 v[86:89], v[166:169], v[198:201], v[86:89]
	v_mfma_f32_16x16x32_bf16 v[82:85], v[174:177], v[198:201], v[82:85]
	v_mfma_f32_16x16x32_bf16 v[70:73], v[166:169], v[212:215], v[70:73]
	v_mfma_f32_16x16x32_bf16 v[66:69], v[174:177], v[212:215], v[66:69]
	s_setprio 0
	s_barrier
	s_add_i32 s12, s12, s39
	s_add_u32 s100, s30, s70
	s_addc_u32 s101, s31, s71
	s_mov_b32 m0, s12
	ds_read_b128 v[178:181], v149 offset:49152
	ds_read_b128 v[182:185], v149 offset:50176
	ds_read_b128 v[186:189], v149 offset:51200
	ds_read_b128 v[190:193], v149 offset:52224
	ds_read_b128 v[194:197], v149 offset:53248
	ds_read_b128 v[198:201], v149 offset:54272
	ds_read_b128 v[202:205], v149 offset:55296
	ds_read_b128 v[212:215], v149 offset:56320
	global_load_lds_dwordx4 v134, s[100:101]
	s_add_i32 m0, s12, 0x2000
	s_add_u32 s30, s30, 0x100080
	s_addc_u32 s31, s31, 0
	s_add_i32 s12, s14, s39
	global_load_lds_dwordx4 v130, s[100:101]
	s_mov_b32 m0, s12
	s_nop 0
	global_load_lds_dwordx4 v134, s[30:31]
	s_add_i32 m0, s12, 0x2000
	s_nop 0
	global_load_lds_dwordx4 v130, s[30:31]
	s_add_u32 s100, s36, s70
	s_addc_u32 s101, s37, s71
	s_mov_b32 m0, s47
	s_nop 0
	global_load_lds_dwordx4 v136, s[100:101]
	s_mov_b32 m0, s48
	s_nop 0
	global_load_lds_dwordx4 v132, s[100:101]
	s_waitcnt vmcnt(8)
	s_waitcnt lgkmcnt(0)
	s_barrier
	s_setprio 1
	s_waitcnt lgkmcnt(0)
	v_mfma_f32_16x16x32_bf16 v[62:65], v[142:145], v[178:181], v[62:65]
	v_mfma_f32_16x16x32_bf16 v[58:61], v[154:157], v[178:181], v[58:61]
	v_mfma_f32_16x16x32_bf16 v[46:49], v[142:145], v[186:189], v[46:49]
	v_mfma_f32_16x16x32_bf16 v[42:45], v[154:157], v[186:189], v[42:45]
	v_mfma_f32_16x16x32_bf16 v[30:33], v[142:145], v[194:197], v[30:33]
	v_mfma_f32_16x16x32_bf16 v[26:29], v[154:157], v[194:197], v[26:29]
	v_mfma_f32_16x16x32_bf16 v[14:17], v[142:145], v[202:205], v[14:17]
	v_mfma_f32_16x16x32_bf16 v[10:13], v[154:157], v[202:205], v[10:13]
	v_mfma_f32_16x16x32_bf16 v[62:65], v[150:153], v[182:185], v[62:65]
	v_mfma_f32_16x16x32_bf16 v[58:61], v[158:161], v[182:185], v[58:61]
	v_mfma_f32_16x16x32_bf16 v[46:49], v[150:153], v[190:193], v[46:49]
	v_mfma_f32_16x16x32_bf16 v[42:45], v[158:161], v[190:193], v[42:45]
	v_mfma_f32_16x16x32_bf16 v[30:33], v[150:153], v[198:201], v[30:33]
	v_mfma_f32_16x16x32_bf16 v[26:29], v[158:161], v[198:201], v[26:29]
	v_mfma_f32_16x16x32_bf16 v[14:17], v[150:153], v[212:215], v[14:17]
	v_mfma_f32_16x16x32_bf16 v[10:13], v[158:161], v[212:215], v[10:13]
	s_setprio 0
	s_setprio 1
	v_mfma_f32_16x16x32_bf16 v[54:57], v[162:165], v[178:181], v[54:57]
	v_mfma_f32_16x16x32_bf16 v[50:53], v[170:173], v[178:181], v[50:53]
	v_mfma_f32_16x16x32_bf16 v[38:41], v[162:165], v[186:189], v[38:41]
	v_mfma_f32_16x16x32_bf16 v[34:37], v[170:173], v[186:189], v[34:37]
	v_mfma_f32_16x16x32_bf16 v[22:25], v[162:165], v[194:197], v[22:25]
	v_mfma_f32_16x16x32_bf16 v[18:21], v[170:173], v[194:197], v[18:21]
	v_mfma_f32_16x16x32_bf16 v[6:9], v[162:165], v[202:205], v[6:9]
	v_mfma_f32_16x16x32_bf16 v[2:5], v[170:173], v[202:205], v[2:5]
	v_mfma_f32_16x16x32_bf16 v[54:57], v[166:169], v[182:185], v[54:57]
	v_mfma_f32_16x16x32_bf16 v[50:53], v[174:177], v[182:185], v[50:53]
	v_mfma_f32_16x16x32_bf16 v[38:41], v[166:169], v[190:193], v[38:41]
	v_mfma_f32_16x16x32_bf16 v[34:37], v[174:177], v[190:193], v[34:37]
	v_mfma_f32_16x16x32_bf16 v[22:25], v[166:169], v[198:201], v[22:25]
	v_mfma_f32_16x16x32_bf16 v[18:21], v[174:177], v[198:201], v[18:21]
	v_mfma_f32_16x16x32_bf16 v[6:9], v[166:169], v[212:215], v[6:9]
	v_mfma_f32_16x16x32_bf16 v[2:5], v[174:177], v[212:215], v[2:5]
	s_setprio 0
	s_barrier
	s_add_i32 s33, s33, 2
	s_add_u32 s6, s6, 0x100
	s_addc_u32 s7, s7, 0
	s_add_u32 s81, s81, 0x100
	s_addc_u32 s54, s54, 0
	s_cmp_gt_u32 s33, 61
	s_cbranch_scc0 .LBB0_348
	s_and_b64 vcc, exec, s[20:21]
	s_cbranch_vccz .LBB0_351
	s_barrier
